# stack23: stack22 + sample-NSA partial-sum reduction loops read 4 LDS pairs per iteration together, gate element requested before the loop
# baseline (speedup 1.0000x reference)
.LBB0_1452:
	s_or_b64 exec, exec, s[0:1]
	v_mov_b32_e32 v204, 0
	ds_write_b128 v148, v[2:5] offset:16896
	ds_write_b128 v148, v[6:9] offset:17152
	ds_write_b128 v148, v[10:13] offset:17408
	ds_write_b128 v148, v[14:17] offset:17664
	s_waitcnt lgkmcnt(0)
	s_barrier
	s_and_saveexec_b64 s[0:1], s[72:73]
	s_cbranch_execz .LBB0_1456
	v_mov_b32_e32 v2, 0
	s_mov_b32 s2, 0
	v_readlane_b32 s98, v247, 50
	v_readlane_b32 s99, v247, 24
	s_nop 0
	v_lshl_or_b32 v50, s98, 2, v142
	v_readlane_b32 s98, v247, 18
	v_mul_u32_u24_e32 v50, 3, v50
	s_add_u32 s98, s98, s5
	s_addc_u32 s99, s99, s4
	v_lshlrev_b32_e32 v50, 1, v50
	s_nop 0
	global_load_ushort v50, v50, s[98:99]
.LBB0_1454:
	v_add_u32_e32 v6, s2, v162
	ds_read2st64_b32 v[4:5], v6 offset1:4
	ds_read2st64_b32 v[42:43], v6 offset0:8 offset1:12
	ds_read2st64_b32 v[44:45], v6 offset0:16 offset1:20
	ds_read2st64_b32 v[46:47], v6 offset0:24 offset1:28
	s_addk_i32 s2, 0x2000
	s_cmpk_eq_u32 s2, 0x8000
	s_waitcnt lgkmcnt(3)
	v_add_f32_e32 v2, v2, v4
	v_add_f32_e32 v2, v2, v5
	s_waitcnt lgkmcnt(2)
	v_add_f32_e32 v2, v2, v42
	v_add_f32_e32 v2, v2, v43
	s_waitcnt lgkmcnt(1)
	v_add_f32_e32 v2, v2, v44
	v_add_f32_e32 v2, v2, v45
	s_waitcnt lgkmcnt(0)
	v_add_f32_e32 v2, v2, v46
	v_add_f32_e32 v2, v2, v47
	s_cbranch_scc0 .LBB0_1454
	s_waitcnt vmcnt(0)
	v_lshlrev_b32_e32 v3, 16, v50
	v_mul_f32_e32 v3, 0xbfb8aa3b, v3
	v_exp_f32_e32 v3, v3
	s_nop 0
	v_add_f32_e32 v3, 1.0, v3
	v_rcp_f32_e32 v3, v3
	s_nop 0
	v_fma_f32 v204, v2, v3, 0

.LBB0_1598:
	s_or_b64 exec, exec, s[0:1]
	ds_write_b128 v148, v[66:69] offset:16896
	ds_write_b128 v148, v[78:81] offset:17152
	ds_write_b128 v148, v[74:77] offset:17408
	ds_write_b128 v148, v[70:73] offset:17664
	s_waitcnt lgkmcnt(0)
	s_barrier
	s_and_saveexec_b64 s[0:1], s[72:73]
	s_cbranch_execz .LBB0_1602
	s_waitcnt vmcnt(7)
	v_mov_b32_e32 v2, 0
	s_mov_b32 s4, 0
	v_readlane_b32 s98, v247, 50
	s_nop 1
	v_lshl_or_b32 v50, s98, 2, v142
	v_mul_u32_u24_e32 v50, 3, v50
	s_add_u32 s98, s43, s2
	s_addc_u32 s99, s42, s3
	v_lshlrev_b32_e32 v50, 1, v50
	global_load_ushort v50, v50, s[98:99]
.LBB0_1600:
	s_waitcnt vmcnt(6)
	v_add_u32_e32 v6, s4, v162
	ds_read2st64_b32 v[4:5], v6 offset1:4
	ds_read2st64_b32 v[42:43], v6 offset0:8 offset1:12
	ds_read2st64_b32 v[44:45], v6 offset0:16 offset1:20
	ds_read2st64_b32 v[46:47], v6 offset0:24 offset1:28
	s_addk_i32 s4, 0x2000
	s_cmpk_eq_u32 s4, 0x8000
	s_waitcnt lgkmcnt(3)
	v_add_f32_e32 v2, v2, v4
	v_add_f32_e32 v2, v2, v5
	s_waitcnt lgkmcnt(2)
	v_add_f32_e32 v2, v2, v42
	v_add_f32_e32 v2, v2, v43
	s_waitcnt lgkmcnt(1)
	v_add_f32_e32 v2, v2, v44
	v_add_f32_e32 v2, v2, v45
	s_waitcnt lgkmcnt(0)
	v_add_f32_e32 v2, v2, v46
	v_add_f32_e32 v2, v2, v47
	s_cbranch_scc0 .LBB0_1600
	s_waitcnt vmcnt(0)
	v_lshlrev_b32_e32 v3, 16, v50
	v_mul_f32_e32 v3, 0xbfb8aa3b, v3
	v_exp_f32_e32 v3, v3
	s_nop 0
	v_add_f32_e32 v3, 1.0, v3
	v_rcp_f32_e32 v3, v3
	s_nop 0
	v_fmac_f32_e32 v204, v2, v3

.LBB0_1648:
	s_or_b64 exec, exec, s[0:1]
	ds_write_b128 v148, v[14:17] offset:16896
	ds_write_b128 v148, v[10:13] offset:17152
	ds_write_b128 v148, v[6:9] offset:17408
	ds_write_b128 v148, v[2:5] offset:17664
	s_waitcnt lgkmcnt(0)
	s_barrier
	s_and_saveexec_b64 s[0:1], s[72:73]
	s_cbranch_execz .LBB0_1652
	v_mov_b32_e32 v2, 0
	s_mov_b32 s4, 0
	v_readlane_b32 s100, v247, 50
	s_add_u32 s98, s92, s2
	s_addc_u32 s99, s27, s3
	v_lshl_or_b32 v50, s100, 2, v142
	v_mul_u32_u24_e32 v50, 3, v50
	v_lshlrev_b32_e32 v50, 1, v50
	global_load_ushort v50, v50, s[98:99]
.LBB0_1650:
	v_add_u32_e32 v6, s4, v162
	ds_read2st64_b32 v[4:5], v6 offset1:4
	ds_read2st64_b32 v[42:43], v6 offset0:8 offset1:12
	ds_read2st64_b32 v[44:45], v6 offset0:16 offset1:20
	ds_read2st64_b32 v[46:47], v6 offset0:24 offset1:28
	s_addk_i32 s4, 0x2000
	s_cmpk_eq_u32 s4, 0x8000
	s_waitcnt lgkmcnt(3)
	v_add_f32_e32 v2, v2, v4
	v_add_f32_e32 v2, v2, v5
	s_waitcnt lgkmcnt(2)
	v_add_f32_e32 v2, v2, v42
	v_add_f32_e32 v2, v2, v43
	s_waitcnt lgkmcnt(1)
	v_add_f32_e32 v2, v2, v44
	v_add_f32_e32 v2, v2, v45
	s_waitcnt lgkmcnt(0)
	v_add_f32_e32 v2, v2, v46
	v_add_f32_e32 v2, v2, v47
	s_cbranch_scc0 .LBB0_1650
	s_waitcnt vmcnt(0)
	v_lshlrev_b32_e32 v3, 16, v50
	v_mul_f32_e32 v3, 0xbfb8aa3b, v3
	v_exp_f32_e32 v3, v3
	s_nop 0
	v_add_f32_e32 v3, 1.0, v3
	v_rcp_f32_e32 v3, v3
	s_nop 0
	v_fmac_f32_e32 v204, v2, v3
